# m0 = wave_base_sgpr + const rewrite extended to the merge branch GEMM (7 GEMM bodies, 187 sites, 73 dead adds removed)
# speedup vs baseline: 1.0012x; 1.0012x over previous
; DI void lds_barrier() { asm volatile("s_waitcnt lgkmcnt(0)\n\ts_barrier" ::: "memory"); }
; DI int tid512() { int t = threadIdx.x; asm volatile("" : "+v"(t)); return t; }
; #define G_BAR __builtin_amdgcn_s_barrier()
;     ...
;   const int t = tid512();
;   const int wid = t >> 6, lane = t & 63, wr = wid >> 2, wc = wid & 3, fr = lane & 15, fq = lane >> 4;
;   int r0, c0, r1, c1;
;   g_stage_rc(t * 16, r0, c0); g_stage_rc(t * 16 + 8192, r1, c1);
;   const int oa0 = r0 * LDA + c0, oa1 = r1 * LDA + c1, ob0 = r0 * LDB + c0, ob1 = r1 * LDB + c1;
;   const int obr = fr * 64 + fq * 16, rdo = obr ^ (((obr >> 9) & 1) << 5);
;   bf16x8 At[4][2], B0[2][2], B1[2][2];
;   constexpr int nt = K / 64;
;   lds_barrier();
;   G_STAGE(G_SB(0, 0), B, ob0, ob1, LDB, 0, KB(0)); G_STAGE(G_SA(0, 0), A, oa0, oa1, LDA, 0, KA(0));
;   G_STAGE(G_SB(0, 1), B, ob0, ob1, LDB, 128, KB(0)); G_STAGE(G_SA(0, 1), A, oa0, oa1, LDA, 128, KA(0));
;   if (wr == 1) G_BAR;
.LBB0_92:
	v_mov_b32_e32 v142, v168
	s_ashr_i32 s25, s24, 31
	s_lshl_b64 s[8:9], s[24:25], 19
	v_lshlrev_b32_e32 v147, 4, v142
	s_nop 0
	v_readfirstlane_b32 s32, v147
	v_and_b32_e32 v2, 32, v142
	v_readlane_b32 s0, v254, 55
	v_lshrrev_b32_e32 v5, 1, v142
	v_bitop3_b32 v2, v147, v2, 48 bitop3:0x6c
	v_readlane_b32 s1, v254, 56
	s_add_u32 s10, s0, s8
	v_ashrrev_i32_e32 v0, 3, v142
	v_lshrrev_b32_e32 v3, 2, v142
	v_and_b32_e32 v14, 32, v5
	v_lshrrev_b32_e32 v15, 1, v2
	v_add_u32_e32 v148, 0x2000, v147
	s_addc_u32 s11, s1, s9
	s_ashr_i32 s23, s22, 31
	v_bfi_b32 v4, 15, v3, v0
	v_or_b32_e32 v2, v15, v14
	v_ashrrev_i32_e32 v17, 7, v148
	s_lshl_b64 s[0:1], s[22:23], 17
	v_bfi_b32 v3, -16, v17, v3
	v_lshl_or_b32 v132, v4, 10, v2
	v_lshl_or_b32 v4, v4, 8, v2
	s_add_u32 s26, s57, s0
	v_lshl_or_b32 v130, v3, 10, v2
	v_lshl_or_b32 v2, v3, 8, v2
	v_ashrrev_i32_e32 v5, 31, v4
	s_addc_u32 s27, s62, s1
	v_lshlrev_b64 v[134:135], 1, v[4:5]
	v_ashrrev_i32_e32 v3, 31, v2
	s_waitcnt lgkmcnt(0)
	s_barrier
	v_lshl_add_u64 v[6:7], s[26:27], 0, v[134:135]
	s_add_u32 m0, s32, 0x10000
	v_lshlrev_b64 v[136:137], 1, v[2:3]
	v_ashrrev_i32_e32 v133, 31, v132
	global_load_lds_dwordx4 v[6:7], off
	v_lshl_add_u64 v[8:9], s[26:27], 0, v[136:137]
	s_add_u32 m0, s32, 0x12000
	v_lshlrev_b64 v[18:19], 1, v[132:133]
	v_ashrrev_i32_e32 v131, 31, v130
	global_load_lds_dwordx4 v[8:9], off
	v_lshl_add_u64 v[10:11], s[10:11], 0, v[18:19]
	s_mov_b32 m0, s32
	v_lshlrev_b64 v[20:21], 1, v[130:131]
	v_readfirstlane_b32 s0, v148
	s_add_u32 s28, s26, 0x10000
	global_load_lds_dwordx4 v[10:11], off
	v_lshl_add_u64 v[12:13], s[10:11], 0, v[20:21]
	s_mov_b32 m0, s0
	s_addc_u32 s29, s27, 0
	global_load_lds_dwordx4 v[12:13], off
	v_lshl_add_u64 v[22:23], s[28:29], 0, v[134:135]
	s_add_u32 m0, s32, 0x14000
	s_nop 0
	global_load_lds_dwordx4 v[22:23], off
	s_add_u32 m0, s32, 0x16000
	s_add_u32 s0, s10, 0x40000
	v_add_u32_e32 v154, 0x4000, v147
	v_lshl_add_u64 v[22:23], s[28:29], 0, v[136:137]
	s_addc_u32 s1, s11, 0
	v_readfirstlane_b32 s12, v154
	global_load_lds_dwordx4 v[22:23], off
	v_lshl_add_u64 v[18:19], s[0:1], 0, v[18:19]
	s_add_u32 m0, s32, 0x4000
	v_add_u32_e32 v155, 0x6000, v147
	global_load_lds_dwordx4 v[18:19], off
	v_lshl_add_u64 v[18:19], s[0:1], 0, v[20:21]
	v_readfirstlane_b32 s0, v155
	s_add_u32 m0, s32, 0x6000
	v_ashrrev_i32_e32 v16, 8, v142
	global_load_lds_dwordx4 v[18:19], off
	v_cmp_eq_u32_e32 vcc, 1, v16
	s_and_saveexec_b64 s[30:31], vcc
	s_cbranch_execz .LBB0_94
	s_barrier
; #define G_WAIT_V(n) asm volatile("s_waitcnt vmcnt(" #n ")" ::: "memory")
; #define G_BAR __builtin_amdgcn_s_barrier()
;     ...
;   G_WAIT_V(4); G_BAR;
;   G_STAGE(G_SB(1, 0), B, ob0, ob1, LDB, 0, KB(1)); G_STAGE(G_SA(1, 0), A, oa0, oa1, LDA, 0, KA(1)); G_STAGE(G_SB(1, 1), B, ob0, ob1, LDB, 128, KB(1));
;   G_WAIT_V(6); G_BAR;
; DI void zero_acc256(f32x4 (&a)[2][2][4][2]) {
; #pragma unroll
;   for (int i = 0; i < 2; ++i)
; #pragma unroll
;     for (int j = 0; j < 2; ++j)
; #pragma unroll
;       for (int m = 0; m < 4; ++m)
; #pragma unroll
;         for (int n = 0; n < 2; ++n)
; #pragma unroll
;           for (int e = 0; e < 4; ++e) a[i][j][m][n][e] = 0.f;
; }
.LBB0_94:
	s_or_b64 exec, exec, s[30:31]
	v_lshl_add_u64 v[6:7], v[6:7], 0, s[76:77]
	s_add_u32 m0, s32, 0x18000
	s_waitcnt vmcnt(4)
	s_barrier
	global_load_lds_dwordx4 v[6:7], off
	v_lshl_add_u64 v[6:7], v[8:9], 0, s[76:77]
	s_add_u32 m0, s32, 0x1a000
	s_nop 0
	global_load_lds_dwordx4 v[6:7], off
	v_lshl_add_u64 v[6:7], v[10:11], 0, s[76:77]
	s_add_u32 m0, s32, 0x8000
	s_nop 0
	global_load_lds_dwordx4 v[6:7], off
	s_add_u32 m0, s32, 0xa000
	s_add_u32 s0, s26, 0x10080
	v_lshl_add_u64 v[6:7], v[12:13], 0, s[76:77]
	s_addc_u32 s1, s27, 0
	global_load_lds_dwordx4 v[6:7], off
	v_lshl_add_u64 v[4:5], v[4:5], 1, s[0:1]
	s_add_u32 m0, s32, 0x1c000
	v_lshl_add_u64 v[2:3], v[2:3], 1, s[0:1]
	global_load_lds_dwordx4 v[4:5], off
	s_add_u32 m0, s32, 0x1e000
	v_bfe_u32 v18, v142, 2, 4
	global_load_lds_dwordx4 v[2:3], off
	v_lshlrev_b32_e32 v2, 10, v17
	v_and_b32_e32 v2, 0xffffc000, v2
	v_lshlrev_b32_e32 v10, 10, v18
	v_lshlrev_b32_e32 v20, 6, v142
	v_or3_b32 v2, v15, v2, v10
	v_lshlrev_b32_e32 v0, 10, v0
	v_and_b32_e32 v19, 48, v142
	v_and_b32_e32 v21, 0x3c0, v20
	v_lshlrev_b32_e32 v23, 2, v142
	v_add_u32_e32 v2, v2, v14
	v_and_b32_e32 v0, 0xffffc000, v0
	v_or_b32_e32 v22, v21, v19
	v_and_b32_e32 v23, 32, v23
	s_mov_b32 s0, 0x14000
	v_ashrrev_i32_e32 v3, 31, v2
	v_or3_b32 v0, v15, v0, v10
	v_bitop3_b32 v6, v22, s0, v23 bitop3:0xde
	s_mov_b32 s0, 0x18000
	v_lshlrev_b64 v[138:139], 1, v[2:3]
	v_add_u32_e32 v2, v0, v14
	s_waitcnt vmcnt(6)
	v_bitop3_b32 v7, v22, s0, v23 bitop3:0xde
	s_mov_b32 s0, 0x1c000
	v_ashrrev_i32_e32 v3, 31, v2
	v_bitop3_b32 v19, v21, v23, v19 bitop3:0x36
	v_bitop3_b32 v4, v22, s88, v23 bitop3:0xde
	v_lshlrev_b32_e32 v5, 13, v16
	v_bitop3_b32 v8, v22, s0, v23 bitop3:0xde
	v_and_b32_e32 v9, 0x3000, v20
	v_lshlrev_b64 v[140:141], 1, v[2:3]
	v_mov_b32_e32 v2, 0
	s_mov_b32 s12, 0
	s_mov_b32 s13, -2
	s_movk_i32 s23, 0xc0
	s_mov_b32 s25, 0x30000
	v_add_u32_e32 v151, v4, v9
	v_add_u32_e32 v143, v19, v5
	v_add_u32_e32 v146, v6, v9
	v_add_u32_e32 v145, v7, v9
	v_add_u32_e32 v144, v8, v9
	s_mov_b64 s[30:31], s[10:11]
	v_mov_b32_e32 v3, v2
	v_mov_b32_e32 v4, v2
	v_mov_b32_e32 v5, v2
	v_mov_b32_e32 v6, v2
	v_mov_b32_e32 v7, v2
	v_mov_b32_e32 v8, v2
	v_mov_b32_e32 v9, v2
	v_mov_b32_e32 v10, v2
	v_mov_b32_e32 v11, v2
	v_mov_b32_e32 v12, v2
	v_mov_b32_e32 v13, v2
	v_mov_b32_e32 v14, v2
	v_mov_b32_e32 v15, v2
	v_mov_b32_e32 v16, v2
	v_mov_b32_e32 v17, v2
	v_mov_b32_e32 v18, v2
	v_mov_b32_e32 v19, v2
	v_mov_b32_e32 v20, v2
	v_mov_b32_e32 v21, v2
	v_mov_b32_e32 v22, v2
	v_mov_b32_e32 v23, v2
	v_mov_b32_e32 v24, v2
	v_mov_b32_e32 v25, v2
	v_mov_b32_e32 v26, v2
	v_mov_b32_e32 v27, v2
	v_mov_b32_e32 v28, v2
	v_mov_b32_e32 v29, v2
	v_mov_b32_e32 v30, v2
	v_mov_b32_e32 v31, v2
	v_mov_b32_e32 v32, v2
	v_mov_b32_e32 v33, v2
	v_mov_b32_e32 v34, v2
	v_mov_b32_e32 v35, v2
	v_mov_b32_e32 v36, v2
	v_mov_b32_e32 v37, v2
	v_mov_b32_e32 v38, v2
	v_mov_b32_e32 v39, v2
	v_mov_b32_e32 v40, v2
	v_mov_b32_e32 v41, v2
	v_mov_b32_e32 v42, v2
	v_mov_b32_e32 v43, v2
	v_mov_b32_e32 v44, v2
	v_mov_b32_e32 v45, v2
	v_mov_b32_e32 v46, v2
	v_mov_b32_e32 v47, v2
	v_mov_b32_e32 v48, v2
	v_mov_b32_e32 v49, v2
	v_mov_b32_e32 v50, v2
	v_mov_b32_e32 v51, v2
	v_mov_b32_e32 v52, v2
	v_mov_b32_e32 v53, v2
	v_mov_b32_e32 v54, v2
	v_mov_b32_e32 v55, v2
	v_mov_b32_e32 v56, v2
	v_mov_b32_e32 v57, v2
	v_mov_b32_e32 v58, v2
	v_mov_b32_e32 v59, v2
	v_mov_b32_e32 v60, v2
	v_mov_b32_e32 v61, v2
	v_mov_b32_e32 v62, v2
	v_mov_b32_e32 v63, v2
	v_mov_b32_e32 v64, v2
	v_mov_b32_e32 v65, v2
	v_mov_b32_e32 v66, v2
	v_mov_b32_e32 v67, v2
	v_mov_b32_e32 v68, v2
	v_mov_b32_e32 v69, v2
	v_mov_b32_e32 v70, v2
	v_mov_b32_e32 v71, v2
	v_mov_b32_e32 v72, v2
	v_mov_b32_e32 v73, v2
	v_mov_b32_e32 v74, v2
	v_mov_b32_e32 v75, v2
	v_mov_b32_e32 v76, v2
	v_mov_b32_e32 v77, v2
	v_mov_b32_e32 v78, v2
	v_mov_b32_e32 v79, v2
	v_mov_b32_e32 v80, v2
	v_mov_b32_e32 v81, v2
	v_mov_b32_e32 v82, v2
	v_mov_b32_e32 v83, v2
	v_mov_b32_e32 v84, v2
	v_mov_b32_e32 v85, v2
	v_mov_b32_e32 v86, v2
	v_mov_b32_e32 v87, v2
	v_mov_b32_e32 v88, v2
	v_mov_b32_e32 v89, v2
	v_mov_b32_e32 v90, v2
	v_mov_b32_e32 v91, v2
	v_mov_b32_e32 v92, v2
	v_mov_b32_e32 v93, v2
	v_mov_b32_e32 v94, v2
	v_mov_b32_e32 v95, v2
	v_mov_b32_e32 v96, v2
	v_mov_b32_e32 v97, v2
	v_mov_b32_e32 v98, v2
	v_mov_b32_e32 v99, v2
	v_mov_b32_e32 v100, v2
	v_mov_b32_e32 v101, v2
	v_mov_b32_e32 v102, v2
	v_mov_b32_e32 v103, v2
	v_mov_b32_e32 v104, v2
	v_mov_b32_e32 v105, v2
	v_mov_b32_e32 v106, v2
	v_mov_b32_e32 v107, v2
	v_mov_b32_e32 v108, v2
	v_mov_b32_e32 v109, v2
	v_mov_b32_e32 v110, v2
	v_mov_b32_e32 v111, v2
	v_mov_b32_e32 v112, v2
	v_mov_b32_e32 v113, v2
	v_mov_b32_e32 v114, v2
	v_mov_b32_e32 v115, v2
	v_mov_b32_e32 v116, v2
	v_mov_b32_e32 v117, v2
	v_mov_b32_e32 v118, v2
	v_mov_b32_e32 v119, v2
	v_mov_b32_e32 v120, v2
	v_mov_b32_e32 v121, v2
	v_mov_b32_e32 v122, v2
	v_mov_b32_e32 v123, v2
	v_mov_b32_e32 v124, v2
	v_mov_b32_e32 v125, v2
	v_mov_b32_e32 v126, v2
	v_mov_b32_e32 v127, v2
	v_mov_b32_e32 v128, v2
	v_mov_b32_e32 v129, v2
	s_barrier
	s_branch .LBB0_96

; #define G_LDA(dst, b, h)                                                                                                  \
;   _Pragma("unroll") for (int m = 0; m < 4; ++m) _Pragma("unroll") for (int k = 0; k < 2; ++k)                             \
;       dst[m][k] = *(const bf16x8*)((const char*)G_SA(b, h) + ((wr * 4 + m) * 2 + k) * 1024 + rdo)
; #define G_LDB(dst, b, h)                                                                                                  \
;   _Pragma("unroll") for (int n = 0; n < 2; ++n) _Pragma("unroll") for (int k = 0; k < 2; ++k)                             \
;       dst[n][k] = *(const bf16x8*)((const char*)G_SB(b, h) + ((wc * 2 + n) * 2 + k) * 1024 + rdo)
; #define G_WAIT_L(n) asm volatile("s_waitcnt lgkmcnt(" #n ")" ::: "memory")
; #define G_BAR __builtin_amdgcn_s_barrier()
; #define G_SCHED __builtin_amdgcn_sched_barrier(0)
;     ...
;   for (int tt = 0; tt < nt - 2; tt += 2) {
;     G_LDB(B0, 0, 0); G_SCHED; G_LDA(At, 0, 0); G_STAGE(G_SA(1, 1), A, oa0, oa1, LDA, 128, KA(tt + 1));
;     G_WAIT_L(8); G_BAR; G_WAIT_L(0); G_MMA(0, 0, At, B0); G_BAR; G_SCHED;
;     G_LDB(B1, 0, 1); G_STAGE(G_SB(0, 0), B, ob0, ob1, LDB, 0, KB(tt + 2));
;     G_BAR; G_WAIT_L(0); G_MMA(0, 1, At, B1); G_BAR;
;     G_LDA(At, 0, 1); G_STAGE(G_SA(0, 0), A, oa0, oa1, LDA, 0, KA(tt + 2));
;     G_BAR; G_WAIT_L(0); G_MMA(1, 0, At, B0); G_BAR; G_SCHED;
.LBB0_96:
	ds_read_b128 v[182:185], v151
	ds_read_b128 v[186:189], v151 offset:1024
	ds_read_b128 v[190:193], v151 offset:2048
	ds_read_b128 v[194:197], v151 offset:3072
	v_lshl_add_u64 v[166:167], s[30:31], 0, v[140:141]
	v_lshl_add_u64 v[164:165], v[166:167], 0, s[78:79]
	s_add_u32 m0, s32, 0xc000
	ds_read_b128 v[198:201], v143
	ds_read_b128 v[202:205], v143 offset:1024
	ds_read_b128 v[206:209], v143 offset:2048
	ds_read_b128 v[210:213], v143 offset:3072
	ds_read_b128 v[214:217], v143 offset:4096
	ds_read_b128 v[218:221], v143 offset:5120
	ds_read_b128 v[222:225], v143 offset:6144
	ds_read_b128 v[226:229], v143 offset:7168
	global_load_lds_dwordx4 v[164:165], off
	v_lshl_add_u64 v[246:247], s[30:31], 0, v[138:139]
	v_lshl_add_u64 v[230:231], v[246:247], 0, s[78:79]
	s_add_u32 m0, s32, 0xe000
	s_add_i32 s34, s13, -1
	global_load_lds_dwordx4 v[230:231], off
	s_waitcnt lgkmcnt(8)
	s_barrier
	s_waitcnt lgkmcnt(0)
	v_mfma_f32_16x16x32_bf16 v[126:129], v[198:201], v[182:185], v[126:129]
	v_mfma_f32_16x16x32_bf16 v[122:125], v[198:201], v[190:193], v[122:125]
	v_mfma_f32_16x16x32_bf16 v[118:121], v[206:209], v[182:185], v[118:121]
	v_mfma_f32_16x16x32_bf16 v[114:117], v[206:209], v[190:193], v[114:117]
	v_mfma_f32_16x16x32_bf16 v[110:113], v[214:217], v[182:185], v[110:113]
	v_mfma_f32_16x16x32_bf16 v[106:109], v[214:217], v[190:193], v[106:109]
	v_mfma_f32_16x16x32_bf16 v[102:105], v[222:225], v[182:185], v[102:105]
	v_mfma_f32_16x16x32_bf16 v[98:101], v[222:225], v[190:193], v[98:101]
	v_mfma_f32_16x16x32_bf16 v[126:129], v[202:205], v[186:189], v[126:129]
	v_mfma_f32_16x16x32_bf16 v[122:125], v[202:205], v[194:197], v[122:125]
	v_mfma_f32_16x16x32_bf16 v[118:121], v[210:213], v[186:189], v[118:121]
	v_mfma_f32_16x16x32_bf16 v[114:117], v[210:213], v[194:197], v[114:117]
	v_mfma_f32_16x16x32_bf16 v[110:113], v[218:221], v[186:189], v[110:113]
	v_mfma_f32_16x16x32_bf16 v[106:109], v[218:221], v[194:197], v[106:109]
	v_mfma_f32_16x16x32_bf16 v[102:105], v[226:229], v[186:189], v[102:105]
	v_mfma_f32_16x16x32_bf16 v[98:101], v[226:229], v[194:197], v[98:101]
	s_barrier
	s_add_i32 s0, s25, 0xffff0000
	s_sub_i32 s1, s23, 64
	s_and_b32 s0, s0, 0x1c0000
	s_and_b32 s1, s1, 0x80
	s_or_b32 s0, s0, s1
	s_lshl_b32 s35, s0, 1
	s_add_u32 s0, s26, s35
	s_addc_u32 s1, s27, 0
	v_lshl_add_u64 v[248:249], s[0:1], 0, v[134:135]
	s_add_u32 m0, s32, 0x10000
	ds_read_b128 v[230:233], v146
	ds_read_b128 v[234:237], v146 offset:1024
	ds_read_b128 v[238:241], v146 offset:2048
	ds_read_b128 v[242:245], v146 offset:3072
	global_load_lds_dwordx4 v[248:249], off
	v_lshl_add_u64 v[248:249], s[0:1], 0, v[136:137]
	s_add_u32 m0, s32, 0x12000
	s_nop 0
	global_load_lds_dwordx4 v[248:249], off
	s_barrier
	s_waitcnt lgkmcnt(0)
	v_mfma_f32_16x16x32_bf16 v[94:97], v[198:201], v[230:233], v[94:97]
	v_mfma_f32_16x16x32_bf16 v[90:93], v[198:201], v[238:241], v[90:93]
	v_mfma_f32_16x16x32_bf16 v[86:89], v[206:209], v[230:233], v[86:89]
	v_mfma_f32_16x16x32_bf16 v[82:85], v[206:209], v[238:241], v[82:85]
	v_mfma_f32_16x16x32_bf16 v[78:81], v[214:217], v[230:233], v[78:81]
	v_mfma_f32_16x16x32_bf16 v[74:77], v[214:217], v[238:241], v[74:77]
	v_mfma_f32_16x16x32_bf16 v[70:73], v[222:225], v[230:233], v[70:73]
	v_mfma_f32_16x16x32_bf16 v[66:69], v[222:225], v[238:241], v[66:69]
	v_mfma_f32_16x16x32_bf16 v[94:97], v[202:205], v[234:237], v[94:97]
	v_mfma_f32_16x16x32_bf16 v[90:93], v[202:205], v[242:245], v[90:93]
	v_mfma_f32_16x16x32_bf16 v[86:89], v[210:213], v[234:237], v[86:89]
	v_mfma_f32_16x16x32_bf16 v[82:85], v[210:213], v[242:245], v[82:85]
	v_mfma_f32_16x16x32_bf16 v[78:81], v[218:221], v[234:237], v[78:81]
	v_mfma_f32_16x16x32_bf16 v[74:77], v[218:221], v[242:245], v[74:77]
	v_mfma_f32_16x16x32_bf16 v[70:73], v[226:229], v[234:237], v[70:73]
	v_mfma_f32_16x16x32_bf16 v[66:69], v[226:229], v[242:245], v[66:69]
	v_lshl_add_u64 v[248:249], v[166:167], 0, s[82:83]
	s_mov_b32 m0, s32
	s_barrier
	ds_read_b128 v[198:201], v143 offset:16384
	ds_read_b128 v[202:205], v143 offset:17408
	ds_read_b128 v[206:209], v143 offset:18432
	ds_read_b128 v[210:213], v143 offset:19456
	ds_read_b128 v[214:217], v143 offset:20480
	ds_read_b128 v[218:221], v143 offset:21504
	ds_read_b128 v[222:225], v143 offset:22528
	ds_read_b128 v[226:229], v143 offset:23552
	global_load_lds_dwordx4 v[248:249], off
	s_add_u32 m0, s32, 0x2000
	v_lshl_add_u64 v[248:249], v[246:247], 0, s[82:83]
	global_load_lds_dwordx4 v[248:249], off
	s_barrier
	s_waitcnt lgkmcnt(0)
	v_mfma_f32_16x16x32_bf16 v[62:65], v[198:201], v[182:185], v[62:65]
	v_mfma_f32_16x16x32_bf16 v[58:61], v[198:201], v[190:193], v[58:61]
	v_mfma_f32_16x16x32_bf16 v[54:57], v[206:209], v[182:185], v[54:57]
	v_mfma_f32_16x16x32_bf16 v[50:53], v[206:209], v[190:193], v[50:53]
	v_mfma_f32_16x16x32_bf16 v[46:49], v[214:217], v[182:185], v[46:49]
	v_mfma_f32_16x16x32_bf16 v[42:45], v[214:217], v[190:193], v[42:45]
	v_mfma_f32_16x16x32_bf16 v[38:41], v[222:225], v[182:185], v[38:41]
	v_mfma_f32_16x16x32_bf16 v[34:37], v[222:225], v[190:193], v[34:37]
	v_mfma_f32_16x16x32_bf16 v[62:65], v[202:205], v[186:189], v[62:65]
	v_mfma_f32_16x16x32_bf16 v[58:61], v[202:205], v[194:197], v[58:61]
	v_mfma_f32_16x16x32_bf16 v[54:57], v[210:213], v[186:189], v[54:57]
	v_mfma_f32_16x16x32_bf16 v[50:53], v[210:213], v[194:197], v[50:53]
	v_mfma_f32_16x16x32_bf16 v[46:49], v[218:221], v[186:189], v[46:49]
	v_mfma_f32_16x16x32_bf16 v[42:45], v[218:221], v[194:197], v[42:45]
	v_mfma_f32_16x16x32_bf16 v[38:41], v[226:229], v[186:189], v[38:41]
	v_mfma_f32_16x16x32_bf16 v[34:37], v[226:229], v[194:197], v[34:37]
	s_barrier
; #define G_LDA(dst, b, h)                                                                                                  \
;   _Pragma("unroll") for (int m = 0; m < 4; ++m) _Pragma("unroll") for (int k = 0; k < 2; ++k)                             \
;       dst[m][k] = *(const bf16x8*)((const char*)G_SA(b, h) + ((wr * 4 + m) * 2 + k) * 1024 + rdo)
; #define G_LDB(dst, b, h)                                                                                                  \
;   _Pragma("unroll") for (int n = 0; n < 2; ++n) _Pragma("unroll") for (int k = 0; k < 2; ++k)                             \
;       dst[n][k] = *(const bf16x8*)((const char*)G_SB(b, h) + ((wc * 2 + n) * 2 + k) * 1024 + rdo)
; #define G_WAIT_V(n) asm volatile("s_waitcnt vmcnt(" #n ")" ::: "memory")
; #define G_WAIT_L(n) asm volatile("s_waitcnt lgkmcnt(" #n ")" ::: "memory")
; #define G_BAR __builtin_amdgcn_s_barrier()
; #define G_SCHED __builtin_amdgcn_sched_barrier(0)
;     ...
;     G_STAGE(G_SB(0, 1), B, ob0, ob1, LDB, 128, KB(tt + 2));
;     G_WAIT_V(6); G_BAR; G_MMA(1, 1, At, B1); G_BAR;
;     G_LDB(B0, 1, 0); G_SCHED; G_LDA(At, 1, 0); G_STAGE(G_SA(0, 1), A, oa0, oa1, LDA, 128, KA(tt + 2));
;     G_WAIT_L(8); G_BAR; G_WAIT_L(0); G_MMA(0, 0, At, B0); G_BAR; G_SCHED;
;     G_LDB(B1, 1, 1); G_STAGE(G_SB(1, 0), B, ob0, ob1, LDB, 0, KB(tt + 3));
;     G_BAR; G_WAIT_L(0); G_MMA(0, 1, At, B1); G_BAR;
;     G_LDA(At, 1, 1); G_STAGE(G_SA(1, 0), A, oa0, oa1, LDA, 0, KA(tt + 3));
	s_add_u32 s0, s28, s35
	s_addc_u32 s1, s29, 0
	s_add_u32 m0, s32, 0x14000
	v_lshl_add_u64 v[182:183], s[0:1], 0, v[134:135]
	global_load_lds_dwordx4 v[182:183], off
	v_lshl_add_u64 v[182:183], s[0:1], 0, v[136:137]
	s_add_u32 m0, s32, 0x16000
	s_nop 0
	global_load_lds_dwordx4 v[182:183], off
	s_waitcnt vmcnt(6)
	s_barrier
	v_mfma_f32_16x16x32_bf16 v[30:33], v[198:201], v[230:233], v[30:33]
	v_mfma_f32_16x16x32_bf16 v[26:29], v[198:201], v[238:241], v[26:29]
	v_mfma_f32_16x16x32_bf16 v[22:25], v[206:209], v[230:233], v[22:25]
	v_mfma_f32_16x16x32_bf16 v[18:21], v[206:209], v[238:241], v[18:21]
	v_mfma_f32_16x16x32_bf16 v[14:17], v[214:217], v[230:233], v[14:17]
	v_mfma_f32_16x16x32_bf16 v[10:13], v[214:217], v[238:241], v[10:13]
	v_mfma_f32_16x16x32_bf16 v[6:9], v[222:225], v[230:233], v[6:9]
	v_mfma_f32_16x16x32_bf16 v[2:5], v[222:225], v[238:241], v[2:5]
	v_mfma_f32_16x16x32_bf16 v[30:33], v[202:205], v[234:237], v[30:33]
	v_mfma_f32_16x16x32_bf16 v[26:29], v[202:205], v[242:245], v[26:29]
	v_mfma_f32_16x16x32_bf16 v[22:25], v[210:213], v[234:237], v[22:25]
	v_mfma_f32_16x16x32_bf16 v[18:21], v[210:213], v[242:245], v[18:21]
	v_mfma_f32_16x16x32_bf16 v[14:17], v[218:221], v[234:237], v[14:17]
	v_mfma_f32_16x16x32_bf16 v[10:13], v[218:221], v[242:245], v[10:13]
	v_mfma_f32_16x16x32_bf16 v[6:9], v[226:229], v[234:237], v[6:9]
	v_mfma_f32_16x16x32_bf16 v[2:5], v[226:229], v[242:245], v[2:5]
	s_barrier
	ds_read_b128 v[182:185], v145
	ds_read_b128 v[186:189], v145 offset:1024
	ds_read_b128 v[190:193], v145 offset:2048
	ds_read_b128 v[194:197], v145 offset:3072
	v_lshl_add_u64 v[230:231], v[166:167], 0, s[86:87]
	s_add_u32 m0, s32, 0x4000
	ds_read_b128 v[198:201], v143 offset:32768
	ds_read_b128 v[202:205], v143 offset:33792
	ds_read_b128 v[206:209], v143 offset:34816
	ds_read_b128 v[210:213], v143 offset:35840
	ds_read_b128 v[214:217], v143 offset:36864
	ds_read_b128 v[218:221], v143 offset:37888
	ds_read_b128 v[222:225], v143 offset:38912
	ds_read_b128 v[226:229], v143 offset:39936
	global_load_lds_dwordx4 v[230:231], off
	s_add_u32 m0, s32, 0x6000
	v_lshl_add_u64 v[230:231], v[246:247], 0, s[86:87]
	global_load_lds_dwordx4 v[230:231], off
	s_waitcnt lgkmcnt(8)
	s_barrier
	s_waitcnt lgkmcnt(0)
	v_mfma_f32_16x16x32_bf16 v[126:129], v[198:201], v[182:185], v[126:129]
	v_mfma_f32_16x16x32_bf16 v[122:125], v[198:201], v[190:193], v[122:125]
	v_mfma_f32_16x16x32_bf16 v[118:121], v[206:209], v[182:185], v[118:121]
	v_mfma_f32_16x16x32_bf16 v[114:117], v[206:209], v[190:193], v[114:117]
	v_mfma_f32_16x16x32_bf16 v[110:113], v[214:217], v[182:185], v[110:113]
	v_mfma_f32_16x16x32_bf16 v[106:109], v[214:217], v[190:193], v[106:109]
	v_mfma_f32_16x16x32_bf16 v[102:105], v[222:225], v[182:185], v[102:105]
	v_mfma_f32_16x16x32_bf16 v[98:101], v[222:225], v[190:193], v[98:101]
	v_mfma_f32_16x16x32_bf16 v[126:129], v[202:205], v[186:189], v[126:129]
	v_mfma_f32_16x16x32_bf16 v[122:125], v[202:205], v[194:197], v[122:125]
	v_mfma_f32_16x16x32_bf16 v[118:121], v[210:213], v[186:189], v[118:121]
	v_mfma_f32_16x16x32_bf16 v[114:117], v[210:213], v[194:197], v[114:117]
	v_mfma_f32_16x16x32_bf16 v[110:113], v[218:221], v[186:189], v[110:113]
	v_mfma_f32_16x16x32_bf16 v[106:109], v[218:221], v[194:197], v[106:109]
	v_mfma_f32_16x16x32_bf16 v[102:105], v[226:229], v[186:189], v[102:105]
	v_mfma_f32_16x16x32_bf16 v[98:101], v[226:229], v[194:197], v[98:101]
	s_barrier
	s_and_b32 s0, s25, 0x1c0000
	s_and_b32 s1, s23, 0xc0
	s_or_b32 s0, s0, s1
	s_lshl_b32 s35, s0, 1
	s_add_u32 s0, s26, s35
	s_addc_u32 s1, s27, 0
	v_lshl_add_u64 v[248:249], s[0:1], 0, v[134:135]
	s_add_u32 m0, s32, 0x18000
	ds_read_b128 v[230:233], v144
	ds_read_b128 v[234:237], v144 offset:1024
	ds_read_b128 v[238:241], v144 offset:2048
	ds_read_b128 v[242:245], v144 offset:3072
	global_load_lds_dwordx4 v[248:249], off
	v_lshl_add_u64 v[248:249], s[0:1], 0, v[136:137]
	s_add_u32 m0, s32, 0x1a000
	s_nop 0
	global_load_lds_dwordx4 v[248:249], off
	s_barrier
	s_waitcnt lgkmcnt(0)
	v_mfma_f32_16x16x32_bf16 v[94:97], v[198:201], v[230:233], v[94:97]
	v_mfma_f32_16x16x32_bf16 v[90:93], v[198:201], v[238:241], v[90:93]
	v_mfma_f32_16x16x32_bf16 v[86:89], v[206:209], v[230:233], v[86:89]
	v_mfma_f32_16x16x32_bf16 v[82:85], v[206:209], v[238:241], v[82:85]
	v_mfma_f32_16x16x32_bf16 v[78:81], v[214:217], v[230:233], v[78:81]
	v_mfma_f32_16x16x32_bf16 v[74:77], v[214:217], v[238:241], v[74:77]
	v_mfma_f32_16x16x32_bf16 v[70:73], v[222:225], v[230:233], v[70:73]
	v_mfma_f32_16x16x32_bf16 v[66:69], v[222:225], v[238:241], v[66:69]
	v_mfma_f32_16x16x32_bf16 v[94:97], v[202:205], v[234:237], v[94:97]
	v_mfma_f32_16x16x32_bf16 v[90:93], v[202:205], v[242:245], v[90:93]
	v_mfma_f32_16x16x32_bf16 v[86:89], v[210:213], v[234:237], v[86:89]
	v_mfma_f32_16x16x32_bf16 v[82:85], v[210:213], v[242:245], v[82:85]
	v_mfma_f32_16x16x32_bf16 v[78:81], v[218:221], v[234:237], v[78:81]
	v_mfma_f32_16x16x32_bf16 v[74:77], v[218:221], v[242:245], v[74:77]
	v_mfma_f32_16x16x32_bf16 v[70:73], v[226:229], v[234:237], v[70:73]
	v_mfma_f32_16x16x32_bf16 v[66:69], v[226:229], v[242:245], v[66:69]
	v_lshl_add_u64 v[166:167], v[166:167], 0, s[90:91]
	s_add_u32 m0, s32, 0x8000
	s_barrier
	ds_read_b128 v[198:201], v143 offset:49152
	ds_read_b128 v[202:205], v143 offset:50176
	ds_read_b128 v[206:209], v143 offset:51200
	ds_read_b128 v[210:213], v143 offset:52224
	ds_read_b128 v[214:217], v143 offset:53248
	ds_read_b128 v[218:221], v143 offset:54272
	ds_read_b128 v[222:225], v143 offset:55296
	ds_read_b128 v[226:229], v143 offset:56320
	global_load_lds_dwordx4 v[166:167], off
	s_add_u32 m0, s32, 0xa000
	v_lshl_add_u64 v[166:167], v[246:247], 0, s[90:91]
	global_load_lds_dwordx4 v[166:167], off
	s_barrier
; DI unsigned pack2(float a, float b) { unsigned r; asm("v_cvt_pk_bf16_f32 %0, %1, %2\n\ts_nop 1" : "=v"(r) : "v"(a), "v"(b)); return r; }
; #define G_WAIT_V(n) asm volatile("s_waitcnt vmcnt(" #n ")" ::: "memory")
; #define G_WAIT_L(n) asm volatile("s_waitcnt lgkmcnt(" #n ")" ::: "memory")
; #define G_BAR __builtin_amdgcn_s_barrier()
; #define G_SCHED __builtin_amdgcn_sched_barrier(0)
; DI u32x4* merge_scratch(PREF p, int region) { const int t = tid512(); return (u32x4*)p.fbuf + (size_t)blockIdx.x * 40960 + region * 8192 + (t >> 6) * 1024 + (t & 63); }
; DI void br_flush(PREF p, f32x4 (&acc)[2][2][4][2], int slot) { br_store(p, acc, slot); zero_acc256(acc); }
;     ...
;     G_BAR; G_WAIT_L(0); G_MMA(1, 0, At, B0); G_BAR; G_SCHED;
;     G_STAGE(G_SB(1, 1), B, ob0, ob1, LDB, 128, KB(tt + 3));
;     G_WAIT_V(6); G_BAR; G_MMA(1, 1, At, B1); G_BAR;
;     if (MODE && ((tt + 1) & 3) == 3) br_flush(p, acc, (tt + 1) >> 2);
; DI void br_store(PREF p, const f32x4 (&acc)[2][2][4][2], int slot) {
;   u32x4* sb = merge_scratch(p, slot);
; #pragma unroll
;   for (int ai = 0; ai < 2; ++ai)
; #pragma unroll
;     for (int bj = 0; bj < 2; ++bj)
; #pragma unroll
;       for (int m = 0; m < 4; ++m) {
;         u32x4 o;
;         o.x = pack2(acc[ai][bj][m][0][0], acc[ai][bj][m][0][1]); o.y = pack2(acc[ai][bj][m][0][2], acc[ai][bj][m][0][3]);
;         o.z = pack2(acc[ai][bj][m][1][0], acc[ai][bj][m][1][1]); o.w = pack2(acc[ai][bj][m][1][2], acc[ai][bj][m][1][3]);
;         sb[((ai * 2 + bj) * 4 + m) * 64] = o;
;       }
; }
	s_waitcnt lgkmcnt(0)
	v_mfma_f32_16x16x32_bf16 v[62:65], v[198:201], v[182:185], v[62:65]
	v_mfma_f32_16x16x32_bf16 v[58:61], v[198:201], v[190:193], v[58:61]
	v_mfma_f32_16x16x32_bf16 v[54:57], v[206:209], v[182:185], v[54:57]
	v_mfma_f32_16x16x32_bf16 v[50:53], v[206:209], v[190:193], v[50:53]
	v_mfma_f32_16x16x32_bf16 v[46:49], v[214:217], v[182:185], v[46:49]
	v_mfma_f32_16x16x32_bf16 v[42:45], v[214:217], v[190:193], v[42:45]
	v_mfma_f32_16x16x32_bf16 v[38:41], v[222:225], v[182:185], v[38:41]
	v_mfma_f32_16x16x32_bf16 v[34:37], v[222:225], v[190:193], v[34:37]
	v_mfma_f32_16x16x32_bf16 v[62:65], v[202:205], v[186:189], v[62:65]
	v_mfma_f32_16x16x32_bf16 v[58:61], v[202:205], v[194:197], v[58:61]
	v_mfma_f32_16x16x32_bf16 v[54:57], v[210:213], v[186:189], v[54:57]
	v_mfma_f32_16x16x32_bf16 v[50:53], v[210:213], v[194:197], v[50:53]
	v_mfma_f32_16x16x32_bf16 v[46:49], v[218:221], v[186:189], v[46:49]
	v_mfma_f32_16x16x32_bf16 v[42:45], v[218:221], v[194:197], v[42:45]
	v_mfma_f32_16x16x32_bf16 v[38:41], v[226:229], v[186:189], v[38:41]
	v_mfma_f32_16x16x32_bf16 v[34:37], v[226:229], v[194:197], v[34:37]
	s_barrier
	s_add_u32 s0, s28, s35
	s_addc_u32 s1, s29, 0
	s_add_u32 m0, s32, 0x1c000
	v_lshl_add_u64 v[166:167], s[0:1], 0, v[134:135]
	global_load_lds_dwordx4 v[166:167], off
	v_lshl_add_u64 v[166:167], s[0:1], 0, v[136:137]
	s_add_u32 m0, s32, 0x1e000
	s_nop 0
	global_load_lds_dwordx4 v[166:167], off
	s_waitcnt vmcnt(6)
	s_barrier
	v_mfma_f32_16x16x32_bf16 v[30:33], v[198:201], v[230:233], v[30:33]
	v_mfma_f32_16x16x32_bf16 v[26:29], v[198:201], v[238:241], v[26:29]
	v_mfma_f32_16x16x32_bf16 v[22:25], v[206:209], v[230:233], v[22:25]
	v_mfma_f32_16x16x32_bf16 v[18:21], v[206:209], v[238:241], v[18:21]
	v_mfma_f32_16x16x32_bf16 v[14:17], v[214:217], v[230:233], v[14:17]
	v_mfma_f32_16x16x32_bf16 v[10:13], v[214:217], v[238:241], v[10:13]
	v_mfma_f32_16x16x32_bf16 v[6:9], v[222:225], v[230:233], v[6:9]
	v_mfma_f32_16x16x32_bf16 v[2:5], v[222:225], v[238:241], v[2:5]
	v_mfma_f32_16x16x32_bf16 v[30:33], v[202:205], v[234:237], v[30:33]
	v_mfma_f32_16x16x32_bf16 v[26:29], v[202:205], v[242:245], v[26:29]
	v_mfma_f32_16x16x32_bf16 v[22:25], v[210:213], v[234:237], v[22:25]
	v_mfma_f32_16x16x32_bf16 v[18:21], v[210:213], v[242:245], v[18:21]
	v_mfma_f32_16x16x32_bf16 v[14:17], v[218:221], v[234:237], v[14:17]
	v_mfma_f32_16x16x32_bf16 v[10:13], v[218:221], v[242:245], v[10:13]
	v_mfma_f32_16x16x32_bf16 v[6:9], v[226:229], v[234:237], v[6:9]
	v_mfma_f32_16x16x32_bf16 v[2:5], v[226:229], v[242:245], v[2:5]
	s_and_b32 s0, s34, 3
	s_cmp_eq_u32 s0, 3
	s_barrier
	s_cbranch_scc0 .LBB0_95
	v_mov_b32_e32 v0, v168
	s_and_b32 s0, s12, 0x6000
	s_lshl_b32 s0, s0, 4
	v_lshlrev_b32_e32 v165, 4, v0
	s_add_u32 s0, s63, s0
	v_and_b32_e32 v166, 0xfffffc00, v165
	s_addc_u32 s1, s64, 0
	v_ashrrev_i32_e32 v167, 31, v166
	v_and_b32_e32 v0, 63, v0
	v_lshl_add_u64 v[166:167], v[166:167], 4, s[0:1]
	v_lshlrev_b32_e32 v0, 4, v0
	v_lshl_add_u64 v[166:167], v[166:167], 0, v[0:1]
	v_cvt_pk_bf16_f32 v94, v94, v95
	v_cvt_pk_bf16_f32 v95, v96, v97
	v_cvt_pk_bf16_f32 v96, v90, v91
	v_add_co_u32_e32 v90, vcc, s80, v166
	v_cvt_pk_bf16_f32 v97, v92, v93
	s_movk_i32 s0, 0x3000
	s_nop 0
	v_addc_co_u32_e32 v91, vcc, 0, v167, vcc
	v_add_co_u32_e32 v92, vcc, s40, v166
	v_cvt_pk_bf16_f32 v30, v30, v31
	v_cvt_pk_bf16_f32 v31, v32, v33
	v_cvt_pk_bf16_f32 v32, v26, v27
	v_cvt_pk_bf16_f32 v126, v126, v127
	s_nop 1
	v_addc_co_u32_e32 v93, vcc, 0, v167, vcc
	v_add_co_u32_e32 v26, vcc, s0, v166
	v_cvt_pk_bf16_f32 v127, v128, v129
	v_cvt_pk_bf16_f32 v128, v122, v123
	v_cvt_pk_bf16_f32 v129, v124, v125
	v_cvt_pk_bf16_f32 v118, v118, v119
	v_cvt_pk_bf16_f32 v119, v120, v121
	v_cvt_pk_bf16_f32 v120, v114, v115
	v_cvt_pk_bf16_f32 v121, v116, v117
	v_cvt_pk_bf16_f32 v110, v110, v111
	v_cvt_pk_bf16_f32 v111, v112, v113
	v_cvt_pk_bf16_f32 v112, v106, v107
	v_cvt_pk_bf16_f32 v113, v108, v109
	v_cvt_pk_bf16_f32 v102, v102, v103
	v_cvt_pk_bf16_f32 v103, v104, v105
	v_cvt_pk_bf16_f32 v104, v98, v99
	v_cvt_pk_bf16_f32 v105, v100, v101
	v_cvt_pk_bf16_f32 v86, v86, v87
	v_cvt_pk_bf16_f32 v87, v88, v89
	v_cvt_pk_bf16_f32 v88, v82, v83
	v_cvt_pk_bf16_f32 v89, v84, v85
	v_cvt_pk_bf16_f32 v78, v78, v79
	v_cvt_pk_bf16_f32 v79, v80, v81
	v_cvt_pk_bf16_f32 v80, v74, v75
	v_cvt_pk_bf16_f32 v81, v76, v77
	v_cvt_pk_bf16_f32 v70, v70, v71
	v_cvt_pk_bf16_f32 v71, v72, v73
	v_cvt_pk_bf16_f32 v72, v66, v67
	v_cvt_pk_bf16_f32 v73, v68, v69
	v_cvt_pk_bf16_f32 v62, v62, v63
	v_cvt_pk_bf16_f32 v63, v64, v65
	v_cvt_pk_bf16_f32 v64, v58, v59
	v_cvt_pk_bf16_f32 v65, v60, v61
	v_cvt_pk_bf16_f32 v54, v54, v55
	v_cvt_pk_bf16_f32 v55, v56, v57
	v_cvt_pk_bf16_f32 v56, v50, v51
	v_cvt_pk_bf16_f32 v57, v52, v53
	v_cvt_pk_bf16_f32 v46, v46, v47
	v_cvt_pk_bf16_f32 v47, v48, v49
	v_cvt_pk_bf16_f32 v48, v42, v43
	v_cvt_pk_bf16_f32 v49, v44, v45
	v_cvt_pk_bf16_f32 v38, v38, v39
	v_cvt_pk_bf16_f32 v39, v40, v41
	v_cvt_pk_bf16_f32 v40, v34, v35
	v_cvt_pk_bf16_f32 v41, v36, v37
	v_cvt_pk_bf16_f32 v33, v28, v29
	s_nop 1
	v_addc_co_u32_e32 v27, vcc, 0, v167, vcc
	v_cvt_pk_bf16_f32 v22, v22, v23
	v_cvt_pk_bf16_f32 v23, v24, v25
	v_cvt_pk_bf16_f32 v24, v18, v19
	v_cvt_pk_bf16_f32 v25, v20, v21
	v_cvt_pk_bf16_f32 v14, v14, v15
	v_cvt_pk_bf16_f32 v15, v16, v17
	v_cvt_pk_bf16_f32 v16, v10, v11
	v_cvt_pk_bf16_f32 v17, v12, v13
	v_cvt_pk_bf16_f32 v6, v6, v7
	v_cvt_pk_bf16_f32 v7, v8, v9
	v_cvt_pk_bf16_f32 v8, v2, v3
	v_cvt_pk_bf16_f32 v9, v4, v5
	v_mov_b32_e32 v2, 0
	global_store_dwordx4 v[166:167], v[126:129], off
	global_store_dwordx4 v[166:167], v[118:121], off offset:1024
	global_store_dwordx4 v[166:167], v[110:113], off offset:2048
; #define G_LDA(dst, b, h)                                                                                                  \
;   _Pragma("unroll") for (int m = 0; m < 4; ++m) _Pragma("unroll") for (int k = 0; k < 2; ++k)                             \
;       dst[m][k] = *(const bf16x8*)((const char*)G_SA(b, h) + ((wr * 4 + m) * 2 + k) * 1024 + rdo)
; #define G_LDB(dst, b, h)                                                                                                  \
;   _Pragma("unroll") for (int n = 0; n < 2; ++n) _Pragma("unroll") for (int k = 0; k < 2; ++k)                             \
;       dst[n][k] = *(const bf16x8*)((const char*)G_SB(b, h) + ((wc * 2 + n) * 2 + k) * 1024 + rdo)
; #define G_WAIT_L(n) asm volatile("s_waitcnt lgkmcnt(" #n ")" ::: "memory")
; #define G_BAR __builtin_amdgcn_s_barrier()
;     ...
;     G_LDB(B0, 0, 0); G_LDA(At, 0, 0); G_STAGE(G_SA(1, 1), A, oa0, oa1, LDA, 128, KA(nt - 1));
;     G_BAR; G_WAIT_L(0); G_MMA(0, 0, At, B0); G_BAR;
; DI void zero_acc256(f32x4 (&a)[2][2][4][2]) {
; #pragma unroll
;   for (int i = 0; i < 2; ++i)
; #pragma unroll
;     for (int j = 0; j < 2; ++j)
; #pragma unroll
;       for (int m = 0; m < 4; ++m)
; #pragma unroll
;         for (int n = 0; n < 2; ++n)
; #pragma unroll
;           for (int e = 0; e < 4; ++e) a[i][j][m][n][e] = 0.f;
; }
	global_store_dwordx4 v[166:167], v[102:105], off offset:3072
	global_store_dwordx4 v[92:93], v[94:97], off offset:-4096
	global_store_dwordx4 v[90:91], v[86:89], off offset:1024
	global_store_dwordx4 v[90:91], v[78:81], off offset:2048
	global_store_dwordx4 v[90:91], v[70:73], off offset:3072
	global_store_dwordx4 v[92:93], v[62:65], off
	global_store_dwordx4 v[92:93], v[54:57], off offset:1024
	global_store_dwordx4 v[92:93], v[46:49], off offset:2048
	global_store_dwordx4 v[92:93], v[38:41], off offset:3072
	global_store_dwordx4 v[26:27], v[30:33], off
	global_store_dwordx4 v[26:27], v[22:25], off offset:1024
	global_store_dwordx4 v[26:27], v[14:17], off offset:2048
	global_store_dwordx4 v[26:27], v[6:9], off offset:3072
	v_mov_b32_e32 v3, v2
	v_mov_b32_e32 v4, v2
	v_mov_b32_e32 v5, v2
	v_mov_b32_e32 v6, v2
	v_mov_b32_e32 v7, v2
	v_mov_b32_e32 v8, v2
	v_mov_b32_e32 v9, v2
	v_mov_b32_e32 v10, v2
	v_mov_b32_e32 v11, v2
	v_mov_b32_e32 v12, v2
	v_mov_b32_e32 v13, v2
	v_mov_b32_e32 v14, v2
	v_mov_b32_e32 v15, v2
	v_mov_b32_e32 v16, v2
	v_mov_b32_e32 v17, v2
	v_mov_b32_e32 v18, v2
	v_mov_b32_e32 v19, v2
	v_mov_b32_e32 v20, v2
	v_mov_b32_e32 v21, v2
	v_mov_b32_e32 v22, v2
	v_mov_b32_e32 v23, v2
	v_mov_b32_e32 v24, v2
	v_mov_b32_e32 v25, v2
	v_mov_b32_e32 v26, v2
	v_mov_b32_e32 v27, v2
	v_mov_b32_e32 v28, v2
	v_mov_b32_e32 v29, v2
	v_mov_b32_e32 v30, v2
	v_mov_b32_e32 v31, v2
	v_mov_b32_e32 v32, v2
	v_mov_b32_e32 v33, v2
	v_mov_b32_e32 v34, v2
	v_mov_b32_e32 v35, v2
	v_mov_b32_e32 v36, v2
	v_mov_b32_e32 v37, v2
	v_mov_b32_e32 v38, v2
	v_mov_b32_e32 v39, v2
	v_mov_b32_e32 v40, v2
	v_mov_b32_e32 v41, v2
	v_mov_b32_e32 v42, v2
	v_mov_b32_e32 v43, v2
	v_mov_b32_e32 v44, v2
	v_mov_b32_e32 v45, v2
	v_mov_b32_e32 v46, v2
	v_mov_b32_e32 v47, v2
	v_mov_b32_e32 v48, v2
	v_mov_b32_e32 v49, v2
	v_mov_b32_e32 v50, v2
	v_mov_b32_e32 v51, v2
	v_mov_b32_e32 v52, v2
	v_mov_b32_e32 v53, v2
	v_mov_b32_e32 v54, v2
	v_mov_b32_e32 v55, v2
	v_mov_b32_e32 v56, v2
	v_mov_b32_e32 v57, v2
	v_mov_b32_e32 v58, v2
	v_mov_b32_e32 v59, v2
	v_mov_b32_e32 v60, v2
	v_mov_b32_e32 v61, v2
	v_mov_b32_e32 v62, v2
	v_mov_b32_e32 v63, v2
	v_mov_b32_e32 v64, v2
	v_mov_b32_e32 v65, v2
	v_mov_b32_e32 v66, v2
	v_mov_b32_e32 v67, v2
	v_mov_b32_e32 v68, v2
	v_mov_b32_e32 v69, v2
	v_mov_b32_e32 v70, v2
	v_mov_b32_e32 v71, v2
	v_mov_b32_e32 v72, v2
	v_mov_b32_e32 v73, v2
	v_mov_b32_e32 v74, v2
	v_mov_b32_e32 v75, v2
	v_mov_b32_e32 v76, v2
	v_mov_b32_e32 v77, v2
	v_mov_b32_e32 v78, v2
	v_mov_b32_e32 v79, v2
	v_mov_b32_e32 v80, v2
	v_mov_b32_e32 v81, v2
	v_mov_b32_e32 v82, v2
	v_mov_b32_e32 v83, v2
	v_mov_b32_e32 v84, v2
	v_mov_b32_e32 v85, v2
	v_mov_b32_e32 v86, v2
	v_mov_b32_e32 v87, v2
	v_mov_b32_e32 v88, v2
	v_mov_b32_e32 v89, v2
	v_mov_b32_e32 v90, v2
	v_mov_b32_e32 v91, v2
	v_mov_b32_e32 v92, v2
	v_mov_b32_e32 v93, v2
	v_mov_b32_e32 v94, v2
	v_mov_b32_e32 v95, v2
	v_mov_b32_e32 v96, v2
	v_mov_b32_e32 v97, v2
	v_mov_b32_e32 v98, v2
	v_mov_b32_e32 v99, v2
	v_mov_b32_e32 v100, v2
	v_mov_b32_e32 v101, v2
	v_mov_b32_e32 v102, v2
	v_mov_b32_e32 v103, v2
	v_mov_b32_e32 v104, v2
	v_mov_b32_e32 v105, v2
	v_mov_b32_e32 v106, v2
	v_mov_b32_e32 v107, v2
	v_mov_b32_e32 v108, v2
	v_mov_b32_e32 v109, v2
	v_mov_b32_e32 v110, v2
	v_mov_b32_e32 v111, v2
	v_mov_b32_e32 v112, v2
	v_mov_b32_e32 v113, v2
	v_mov_b32_e32 v114, v2
	v_mov_b32_e32 v115, v2
	v_mov_b32_e32 v116, v2
	v_mov_b32_e32 v117, v2
	v_mov_b32_e32 v118, v2
	v_mov_b32_e32 v119, v2
	v_mov_b32_e32 v120, v2
	v_mov_b32_e32 v121, v2
	v_mov_b32_e32 v122, v2
	v_mov_b32_e32 v123, v2
	v_mov_b32_e32 v124, v2
	v_mov_b32_e32 v125, v2
	v_mov_b32_e32 v126, v2
	v_mov_b32_e32 v127, v2
	v_mov_b32_e32 v128, v2
	v_mov_b32_e32 v129, v2
	s_branch .LBB0_95
.LBB0_98:
	s_add_u32 s0, s10, 0x40780
	s_addc_u32 s1, s11, 0
	v_lshl_add_u64 v[132:133], v[132:133], 1, s[0:1]
	s_add_u32 m0, s32, 0xc000
	v_lshl_add_u64 v[130:131], v[130:131], 1, s[0:1]
	ds_read_b128 v[134:137], v151
	ds_read_b128 v[138:141], v151 offset:1024
	ds_read_b128 v[152:155], v151 offset:2048
	ds_read_b128 v[148:151], v151 offset:3072
	ds_read_b128 v[156:159], v143
	ds_read_b128 v[182:185], v143 offset:1024
	ds_read_b128 v[186:189], v143 offset:2048
	ds_read_b128 v[190:193], v143 offset:3072
	ds_read_b128 v[194:197], v143 offset:4096
	ds_read_b128 v[198:201], v143 offset:5120
	ds_read_b128 v[202:205], v143 offset:6144
	ds_read_b128 v[206:209], v143 offset:7168
	global_load_lds_dwordx4 v[132:133], off
	s_add_u32 m0, s32, 0xe000
	s_nop 0
	global_load_lds_dwordx4 v[130:131], off
	s_barrier
	s_waitcnt lgkmcnt(0)
	v_mfma_f32_16x16x32_bf16 v[126:129], v[156:159], v[134:137], v[126:129]
	v_mfma_f32_16x16x32_bf16 v[122:125], v[156:159], v[152:155], v[122:125]
	v_mfma_f32_16x16x32_bf16 v[118:121], v[186:189], v[134:137], v[118:121]
	v_mfma_f32_16x16x32_bf16 v[114:117], v[186:189], v[152:155], v[114:117]
	v_mfma_f32_16x16x32_bf16 v[110:113], v[194:197], v[134:137], v[110:113]
	v_mfma_f32_16x16x32_bf16 v[106:109], v[194:197], v[152:155], v[106:109]
	v_mfma_f32_16x16x32_bf16 v[102:105], v[202:205], v[134:137], v[102:105]
	v_mfma_f32_16x16x32_bf16 v[98:101], v[202:205], v[152:155], v[98:101]
	v_mfma_f32_16x16x32_bf16 v[126:129], v[182:185], v[138:141], v[126:129]
	v_mfma_f32_16x16x32_bf16 v[122:125], v[182:185], v[148:151], v[122:125]
	v_mfma_f32_16x16x32_bf16 v[118:121], v[190:193], v[138:141], v[118:121]
	v_mfma_f32_16x16x32_bf16 v[114:117], v[190:193], v[148:151], v[114:117]
	v_mfma_f32_16x16x32_bf16 v[110:113], v[198:201], v[138:141], v[110:113]
	v_mfma_f32_16x16x32_bf16 v[106:109], v[198:201], v[148:151], v[106:109]
	v_mfma_f32_16x16x32_bf16 v[102:105], v[206:209], v[138:141], v[102:105]
	v_mfma_f32_16x16x32_bf16 v[98:101], v[206:209], v[148:151], v[98:101]
	s_barrier
; #define G_LDA(dst, b, h)                                                                                                  \
;   _Pragma("unroll") for (int m = 0; m < 4; ++m) _Pragma("unroll") for (int k = 0; k < 2; ++k)                             \
;       dst[m][k] = *(const bf16x8*)((const char*)G_SA(b, h) + ((wr * 4 + m) * 2 + k) * 1024 + rdo)
; #define G_LDB(dst, b, h)                                                                                                  \
;   _Pragma("unroll") for (int n = 0; n < 2; ++n) _Pragma("unroll") for (int k = 0; k < 2; ++k)                             \
;       dst[n][k] = *(const bf16x8*)((const char*)G_SB(b, h) + ((wc * 2 + n) * 2 + k) * 1024 + rdo)
; #define G_WAIT_V(n) asm volatile("s_waitcnt vmcnt(" #n ")" ::: "memory")
; #define G_WAIT_L(n) asm volatile("s_waitcnt lgkmcnt(" #n ")" ::: "memory")
; #define G_BAR __builtin_amdgcn_s_barrier()
;     ...
;     G_BAR; G_WAIT_L(0); G_MMA(0, 0, At, B0); G_BAR;
;     G_LDB(B1, 0, 1); G_BAR; G_WAIT_L(0); G_MMA(0, 1, At, B1); G_BAR;
;     G_LDA(At, 0, 1); G_WAIT_V(4); G_BAR; G_WAIT_L(0); G_MMA(1, 0, At, B0); G_MMA(1, 1, At, B1); G_BAR;
;   }
;   {
;     G_LDB(B0, 1, 0); G_LDA(At, 1, 0); G_WAIT_V(2); G_BAR; G_WAIT_L(0); G_MMA(0, 0, At, B0); G_BAR;
	ds_read_b128 v[130:133], v146
	ds_read_b128 v[164:167], v146 offset:1024
	ds_read_b128 v[210:213], v146 offset:2048
	ds_read_b128 v[214:217], v146 offset:3072
	s_barrier
	s_waitcnt lgkmcnt(0)
	v_mfma_f32_16x16x32_bf16 v[90:93], v[156:159], v[210:213], v[90:93]
	v_mfma_f32_16x16x32_bf16 v[86:89], v[186:189], v[130:133], v[86:89]
	v_mfma_f32_16x16x32_bf16 v[82:85], v[186:189], v[210:213], v[82:85]
	v_mfma_f32_16x16x32_bf16 v[78:81], v[194:197], v[130:133], v[78:81]
	v_mfma_f32_16x16x32_bf16 v[74:77], v[194:197], v[210:213], v[74:77]
	v_mfma_f32_16x16x32_bf16 v[70:73], v[202:205], v[130:133], v[70:73]
	v_mfma_f32_16x16x32_bf16 v[94:97], v[156:159], v[130:133], v[94:97]
	v_mfma_f32_16x16x32_bf16 v[90:93], v[182:185], v[214:217], v[90:93]
	v_mfma_f32_16x16x32_bf16 v[86:89], v[190:193], v[164:167], v[86:89]
	v_mfma_f32_16x16x32_bf16 v[82:85], v[190:193], v[214:217], v[82:85]
	v_mfma_f32_16x16x32_bf16 v[78:81], v[198:201], v[164:167], v[78:81]
	v_mfma_f32_16x16x32_bf16 v[74:77], v[198:201], v[214:217], v[74:77]
	v_mfma_f32_16x16x32_bf16 v[70:73], v[206:209], v[164:167], v[70:73]
	v_mfma_f32_16x16x32_bf16 v[66:69], v[202:205], v[210:213], v[66:69]
	v_mfma_f32_16x16x32_bf16 v[218:221], v[182:185], v[164:167], v[94:97]
	v_mfma_f32_16x16x32_bf16 v[156:159], v[206:209], v[214:217], v[66:69]
	s_barrier
	s_nop 3
	s_nop 0
	ds_read_b128 v[66:69], v143 offset:16384
	ds_read_b128 v[94:97], v143 offset:17408
	ds_read_b128 v[182:185], v143 offset:18432
	ds_read_b128 v[186:189], v143 offset:19456
	ds_read_b128 v[190:193], v143 offset:20480
	ds_read_b128 v[194:197], v143 offset:21504
	ds_read_b128 v[198:201], v143 offset:22528
	ds_read_b128 v[202:205], v143 offset:23552
	s_waitcnt vmcnt(4)
	s_barrier
	s_waitcnt lgkmcnt(0)
	v_mfma_f32_16x16x32_bf16 v[62:65], v[66:69], v[134:137], v[62:65]
	v_mfma_f32_16x16x32_bf16 v[54:57], v[182:185], v[134:137], v[54:57]
	v_mfma_f32_16x16x32_bf16 v[50:53], v[182:185], v[152:155], v[50:53]
	v_mfma_f32_16x16x32_bf16 v[46:49], v[190:193], v[134:137], v[46:49]
	v_mfma_f32_16x16x32_bf16 v[42:45], v[190:193], v[152:155], v[42:45]
	v_mfma_f32_16x16x32_bf16 v[38:41], v[198:201], v[134:137], v[38:41]
	v_mfma_f32_16x16x32_bf16 v[34:37], v[198:201], v[152:155], v[34:37]
	v_mfma_f32_16x16x32_bf16 v[62:65], v[94:97], v[138:141], v[62:65]
	v_mfma_f32_16x16x32_bf16 v[58:61], v[66:69], v[152:155], v[58:61]
	v_mfma_f32_16x16x32_bf16 v[54:57], v[186:189], v[138:141], v[54:57]
	v_mfma_f32_16x16x32_bf16 v[50:53], v[186:189], v[148:151], v[50:53]
	v_mfma_f32_16x16x32_bf16 v[46:49], v[194:197], v[138:141], v[46:49]
	v_mfma_f32_16x16x32_bf16 v[42:45], v[194:197], v[148:151], v[42:45]
	v_mfma_f32_16x16x32_bf16 v[38:41], v[202:205], v[138:141], v[38:41]
	v_mfma_f32_16x16x32_bf16 v[34:37], v[202:205], v[148:151], v[34:37]
	v_mfma_f32_16x16x32_bf16 v[206:209], v[94:97], v[148:151], v[58:61]
	v_mfma_f32_16x16x32_bf16 v[30:33], v[66:69], v[130:133], v[30:33]
	v_mfma_f32_16x16x32_bf16 v[26:29], v[66:69], v[210:213], v[26:29]
	v_mfma_f32_16x16x32_bf16 v[22:25], v[182:185], v[130:133], v[22:25]
	v_mfma_f32_16x16x32_bf16 v[18:21], v[182:185], v[210:213], v[18:21]
	v_mfma_f32_16x16x32_bf16 v[14:17], v[190:193], v[130:133], v[14:17]
	v_mfma_f32_16x16x32_bf16 v[10:13], v[190:193], v[210:213], v[10:13]
	v_mfma_f32_16x16x32_bf16 v[6:9], v[198:201], v[130:133], v[6:9]
	v_mfma_f32_16x16x32_bf16 v[2:5], v[198:201], v[210:213], v[2:5]
	v_mfma_f32_16x16x32_bf16 v[30:33], v[94:97], v[164:167], v[30:33]
	v_mfma_f32_16x16x32_bf16 v[26:29], v[94:97], v[214:217], v[26:29]
	v_mfma_f32_16x16x32_bf16 v[22:25], v[186:189], v[164:167], v[22:25]
	v_mfma_f32_16x16x32_bf16 v[18:21], v[186:189], v[214:217], v[18:21]
	v_mfma_f32_16x16x32_bf16 v[14:17], v[194:197], v[164:167], v[14:17]
	v_mfma_f32_16x16x32_bf16 v[10:13], v[194:197], v[214:217], v[10:13]
	v_mfma_f32_16x16x32_bf16 v[6:9], v[202:205], v[164:167], v[6:9]
	v_mfma_f32_16x16x32_bf16 v[2:5], v[202:205], v[214:217], v[2:5]
	s_barrier
	ds_read_b128 v[130:133], v145
	ds_read_b128 v[134:137], v145 offset:1024
	ds_read_b128 v[138:141], v145 offset:2048
	ds_read_b128 v[146:149], v145 offset:3072
	ds_read_b128 v[58:61], v143 offset:32768
	ds_read_b128 v[66:69], v143 offset:33792
	ds_read_b128 v[150:153], v143 offset:34816
	ds_read_b128 v[164:167], v143 offset:35840
	ds_read_b128 v[182:185], v143 offset:36864
	ds_read_b128 v[186:189], v143 offset:37888
	ds_read_b128 v[190:193], v143 offset:38912
	ds_read_b128 v[194:197], v143 offset:39936
	s_waitcnt vmcnt(2)
	s_barrier
; #define G_LDA(dst, b, h)                                                                                                  \
;   _Pragma("unroll") for (int m = 0; m < 4; ++m) _Pragma("unroll") for (int k = 0; k < 2; ++k)                             \
;       dst[m][k] = *(const bf16x8*)((const char*)G_SA(b, h) + ((wr * 4 + m) * 2 + k) * 1024 + rdo)
; #define G_LDB(dst, b, h)                                                                                                  \
;   _Pragma("unroll") for (int n = 0; n < 2; ++n) _Pragma("unroll") for (int k = 0; k < 2; ++k)                             \
;       dst[n][k] = *(const bf16x8*)((const char*)G_SB(b, h) + ((wc * 2 + n) * 2 + k) * 1024 + rdo)
; #define G_WAIT_V(n) asm volatile("s_waitcnt vmcnt(" #n ")" ::: "memory")
; #define G_WAIT_L(n) asm volatile("s_waitcnt lgkmcnt(" #n ")" ::: "memory")
; #define G_BAR __builtin_amdgcn_s_barrier()
;     ...
;     G_LDB(B0, 1, 0); G_LDA(At, 1, 0); G_WAIT_V(2); G_BAR; G_WAIT_L(0); G_MMA(0, 0, At, B0); G_BAR;
;     G_LDB(B1, 1, 1); G_WAIT_V(0); G_BAR; G_WAIT_L(0); G_MMA(0, 1, At, B1); G_BAR;
;     G_LDA(At, 1, 1); G_BAR; G_WAIT_L(0); G_MMA(1, 0, At, B0); G_MMA(1, 1, At, B1); G_BAR;
;   }
;   if (wr == 0) G_BAR;
	s_waitcnt lgkmcnt(0)
	v_mfma_f32_16x16x32_bf16 v[94:97], v[58:61], v[130:133], v[126:129]
	v_mfma_f32_16x16x32_bf16 v[126:129], v[66:69], v[134:137], v[94:97]
	v_mfma_f32_16x16x32_bf16 v[94:97], v[58:61], v[138:141], v[122:125]
	v_mfma_f32_16x16x32_bf16 v[122:125], v[66:69], v[146:149], v[94:97]
	v_mfma_f32_16x16x32_bf16 v[94:97], v[150:153], v[130:133], v[118:121]
	v_mfma_f32_16x16x32_bf16 v[118:121], v[164:167], v[134:137], v[94:97]
	v_mfma_f32_16x16x32_bf16 v[94:97], v[150:153], v[138:141], v[114:117]
	v_mfma_f32_16x16x32_bf16 v[114:117], v[164:167], v[146:149], v[94:97]
	v_mfma_f32_16x16x32_bf16 v[94:97], v[182:185], v[130:133], v[110:113]
	v_mfma_f32_16x16x32_bf16 v[110:113], v[186:189], v[134:137], v[94:97]
	v_mfma_f32_16x16x32_bf16 v[94:97], v[182:185], v[138:141], v[106:109]
	v_mfma_f32_16x16x32_bf16 v[106:109], v[186:189], v[146:149], v[94:97]
	v_mfma_f32_16x16x32_bf16 v[94:97], v[190:193], v[130:133], v[102:105]
	v_mfma_f32_16x16x32_bf16 v[102:105], v[194:197], v[134:137], v[94:97]
	v_mfma_f32_16x16x32_bf16 v[94:97], v[190:193], v[138:141], v[98:101]
	v_mfma_f32_16x16x32_bf16 v[94:97], v[194:197], v[146:149], v[94:97]
	s_barrier
	ds_read_b128 v[198:201], v144
	ds_read_b128 v[202:205], v144 offset:1024
	ds_read_b128 v[210:213], v144 offset:2048
	ds_read_b128 v[214:217], v144 offset:3072
	s_waitcnt vmcnt(0)
	s_barrier
	s_waitcnt lgkmcnt(0)
	v_mfma_f32_16x16x32_bf16 v[98:101], v[58:61], v[198:201], v[218:221]
	v_mfma_f32_16x16x32_bf16 v[58:61], v[58:61], v[210:213], v[90:93]
	v_mfma_f32_16x16x32_bf16 v[90:93], v[66:69], v[214:217], v[58:61]
	v_mfma_f32_16x16x32_bf16 v[58:61], v[150:153], v[198:201], v[86:89]
	v_mfma_f32_16x16x32_bf16 v[86:89], v[164:167], v[202:205], v[58:61]
	v_mfma_f32_16x16x32_bf16 v[58:61], v[150:153], v[210:213], v[82:85]
	v_mfma_f32_16x16x32_bf16 v[82:85], v[164:167], v[214:217], v[58:61]
	v_mfma_f32_16x16x32_bf16 v[58:61], v[182:185], v[198:201], v[78:81]
	v_mfma_f32_16x16x32_bf16 v[78:81], v[186:189], v[202:205], v[58:61]
	v_mfma_f32_16x16x32_bf16 v[58:61], v[182:185], v[210:213], v[74:77]
	v_mfma_f32_16x16x32_bf16 v[74:77], v[186:189], v[214:217], v[58:61]
	v_mfma_f32_16x16x32_bf16 v[58:61], v[190:193], v[198:201], v[70:73]
	v_mfma_f32_16x16x32_bf16 v[98:101], v[66:69], v[202:205], v[98:101]
	v_mfma_f32_16x16x32_bf16 v[66:69], v[194:197], v[202:205], v[58:61]
	v_mfma_f32_16x16x32_bf16 v[58:61], v[190:193], v[210:213], v[156:159]
	v_mfma_f32_16x16x32_bf16 v[58:61], v[194:197], v[214:217], v[58:61]
	s_barrier
	ds_read_b128 v[150:153], v143 offset:49152
	ds_read_b128 v[154:157], v143 offset:50176
	ds_read_b128 v[158:161], v143 offset:51200
	ds_read_b128 v[164:167], v143 offset:52224
	ds_read_b128 v[182:185], v143 offset:53248
	ds_read_b128 v[186:189], v143 offset:54272
	ds_read_b128 v[190:193], v143 offset:55296
	ds_read_b128 v[194:197], v143 offset:56320
	s_barrier
	s_waitcnt lgkmcnt(0)
	v_mfma_f32_16x16x32_bf16 v[62:65], v[150:153], v[130:133], v[62:65]
	v_mfma_f32_16x16x32_bf16 v[70:73], v[154:157], v[134:137], v[62:65]
	v_mfma_f32_16x16x32_bf16 v[62:65], v[150:153], v[138:141], v[206:209]
	v_mfma_f32_16x16x32_bf16 v[54:57], v[158:161], v[130:133], v[54:57]
	v_mfma_f32_16x16x32_bf16 v[50:53], v[158:161], v[138:141], v[50:53]
	v_mfma_f32_16x16x32_bf16 v[46:49], v[182:185], v[130:133], v[46:49]
	v_mfma_f32_16x16x32_bf16 v[42:45], v[182:185], v[138:141], v[42:45]
	v_mfma_f32_16x16x32_bf16 v[38:41], v[190:193], v[130:133], v[38:41]
	v_mfma_f32_16x16x32_bf16 v[34:37], v[190:193], v[138:141], v[34:37]
	v_mfma_f32_16x16x32_bf16 v[62:65], v[154:157], v[146:149], v[62:65]
	v_mfma_f32_16x16x32_bf16 v[54:57], v[164:167], v[134:137], v[54:57]
	v_mfma_f32_16x16x32_bf16 v[50:53], v[164:167], v[146:149], v[50:53]
	v_mfma_f32_16x16x32_bf16 v[46:49], v[186:189], v[134:137], v[46:49]
	v_mfma_f32_16x16x32_bf16 v[42:45], v[186:189], v[146:149], v[42:45]
	v_mfma_f32_16x16x32_bf16 v[38:41], v[194:197], v[134:137], v[38:41]
	v_mfma_f32_16x16x32_bf16 v[34:37], v[194:197], v[146:149], v[34:37]
	v_mfma_f32_16x16x32_bf16 v[30:33], v[150:153], v[198:201], v[30:33]
	v_mfma_f32_16x16x32_bf16 v[26:29], v[150:153], v[210:213], v[26:29]
	v_mfma_f32_16x16x32_bf16 v[22:25], v[158:161], v[198:201], v[22:25]
	v_mfma_f32_16x16x32_bf16 v[18:21], v[158:161], v[210:213], v[18:21]
	v_mfma_f32_16x16x32_bf16 v[14:17], v[182:185], v[198:201], v[14:17]
	v_mfma_f32_16x16x32_bf16 v[10:13], v[182:185], v[210:213], v[10:13]
	v_mfma_f32_16x16x32_bf16 v[6:9], v[190:193], v[198:201], v[6:9]
	v_mfma_f32_16x16x32_bf16 v[2:5], v[190:193], v[210:213], v[2:5]
	v_mfma_f32_16x16x32_bf16 v[30:33], v[154:157], v[202:205], v[30:33]
	v_mfma_f32_16x16x32_bf16 v[26:29], v[154:157], v[214:217], v[26:29]
	v_mfma_f32_16x16x32_bf16 v[22:25], v[164:167], v[202:205], v[22:25]
	v_mfma_f32_16x16x32_bf16 v[18:21], v[164:167], v[214:217], v[18:21]
	v_mfma_f32_16x16x32_bf16 v[14:17], v[186:189], v[202:205], v[14:17]
	v_mfma_f32_16x16x32_bf16 v[10:13], v[186:189], v[214:217], v[10:13]
	v_mfma_f32_16x16x32_bf16 v[6:9], v[194:197], v[202:205], v[6:9]
	v_mfma_f32_16x16x32_bf16 v[2:5], v[194:197], v[214:217], v[2:5]
	v_cmp_gt_u32_e32 vcc, s67, v142
	s_barrier
	s_and_saveexec_b64 s[10:11], vcc
	s_cbranch_execz .LBB0_100
	s_barrier
